# software-pipelined K-fragment LDS reads in all 7 attention QK blocks (depth 6-8 using free VGPRs)
# speedup vs baseline: 1.0123x; 1.0123x over previous
.LBB0_861:
	s_lshl_b32 s10, s16, 14
	s_add_i32 s10, s10, 0
	s_add_i32 s10, s10, 0x10000
	v_add3_u32 v0, s10, v155, v154
	v_add3_u32 v6, s10, v157, v154
	v_add3_u32 v7, s10, v158, v154
	v_add3_u32 v8, s10, v159, v154
	ds_read_b128 v[216:219], v0
	ds_read_b128 v[220:223], v0 offset:8192
	ds_read_b128 v[224:227], v6
	ds_read_b128 v[228:231], v6 offset:8192
	ds_read_b128 v[232:235], v7
	ds_read_b128 v[236:239], v7 offset:8192
	ds_read_b128 v[240:243], v8
	ds_read_b128 v[244:247], v8 offset:8192
	s_waitcnt lgkmcnt(6)
	v_mfma_f32_32x32x16_bf16 v[96:111], v[216:219], v[112:115], 0
	v_mfma_f32_32x32x16_bf16 v[80:95], v[220:223], v[112:115], 0
	ds_read_b128 v[216:219], v0 offset:128
	ds_read_b128 v[220:223], v0 offset:8320
	s_waitcnt lgkmcnt(6)
	v_mfma_f32_32x32x16_bf16 v[96:111], v[224:227], v[116:119], v[96:111]
	v_mfma_f32_32x32x16_bf16 v[80:95], v[228:231], v[116:119], v[80:95]
	ds_read_b128 v[224:227], v6 offset:128
	ds_read_b128 v[228:231], v6 offset:8320
	s_waitcnt lgkmcnt(6)
	v_mfma_f32_32x32x16_bf16 v[96:111], v[232:235], v[120:123], v[96:111]
	v_mfma_f32_32x32x16_bf16 v[80:95], v[236:239], v[120:123], v[80:95]
	ds_read_b128 v[232:235], v7 offset:128
	ds_read_b128 v[236:239], v7 offset:8320
	s_waitcnt lgkmcnt(6)
	v_mfma_f32_32x32x16_bf16 v[96:111], v[240:243], v[124:127], v[96:111]
	v_mfma_f32_32x32x16_bf16 v[80:95], v[244:247], v[124:127], v[80:95]
	ds_read_b128 v[240:243], v8 offset:128
	ds_read_b128 v[244:247], v8 offset:8320
	s_andn2_b64 vcc, exec, s[6:7]
	s_waitcnt lgkmcnt(6)
	v_mfma_f32_32x32x16_bf16 v[96:111], v[216:219], v[128:131], v[96:111]
	v_mfma_f32_32x32x16_bf16 v[80:95], v[220:223], v[128:131], v[80:95]
	s_waitcnt lgkmcnt(4)
	v_mfma_f32_32x32x16_bf16 v[96:111], v[224:227], v[132:135], v[96:111]
	v_mfma_f32_32x32x16_bf16 v[80:95], v[228:231], v[132:135], v[80:95]
	s_waitcnt lgkmcnt(2)
	v_mfma_f32_32x32x16_bf16 v[96:111], v[232:235], v[136:139], v[96:111]
	v_mfma_f32_32x32x16_bf16 v[80:95], v[236:239], v[136:139], v[80:95]
	s_waitcnt lgkmcnt(0)
	v_mfma_f32_32x32x16_bf16 v[96:111], v[240:243], v[140:143], v[96:111]
	v_mfma_f32_32x32x16_bf16 v[80:95], v[244:247], v[140:143], v[80:95]
	s_nop 1
	s_cbranch_vccnz .LBB0_871
	s_nop 7
	v_max_f32_e32 v0, v97, v97
	v_max_f32_e32 v2, v96, v96
	v_max_f32_e32 v0, v2, v0
	v_max3_f32 v0, v0, v98, v99
	v_max3_f32 v0, v0, v100, v101
	v_max3_f32 v0, v0, v102, v103
	v_max3_f32 v0, v0, v104, v105
	v_max3_f32 v0, v0, v106, v107
	v_max3_f32 v0, v0, v108, v109
	v_max3_f32 v0, v0, v110, v111
	v_max3_f32 v0, v0, v80, v81
	v_max3_f32 v0, v0, v82, v83
	v_max3_f32 v0, v0, v84, v85
	v_max3_f32 v0, v0, v86, v87
	v_max3_f32 v0, v0, v88, v89
	v_max3_f32 v0, v0, v90, v91
	v_max3_f32 v0, v0, v92, v93
	v_max3_f32 v0, v0, v94, v95
	v_mov_b32_e32 v2, v0
	s_nop 1
	v_permlane32_swap_b32_e32 v0, v2
	v_max_f32_e32 v2, v2, v2
	v_max_f32_e32 v0, v0, v0
	v_max_f32_e32 v0, v0, v2
	v_sub_f32_e32 v2, v0, v156
	v_cmp_ge_f32_e32 vcc, s86, v2
	s_cmp_eq_u64 vcc, exec
	v_max_f32_e32 v2, v156, v156
	v_max_f32_e32 v2, v2, v0
	s_cselect_b64 vcc, -1, 0
	v_sub_f32_e32 v0, v156, v2
	v_cndmask_b32_e32 v156, v2, v156, vcc
	v_sub_f32_e32 v2, v96, v156
	v_exp_f32_e32 v96, v2
	v_sub_f32_e32 v2, v80, v156
	v_exp_f32_e32 v80, v2
	v_sub_f32_e32 v2, v97, v156
	v_exp_f32_e32 v97, v2
	v_sub_f32_e32 v2, v81, v156
	v_exp_f32_e32 v81, v2
	v_sub_f32_e32 v2, v98, v156
	v_exp_f32_e32 v98, v2
	v_sub_f32_e32 v2, v82, v156
	v_exp_f32_e32 v82, v2
	v_sub_f32_e32 v2, v99, v156
	v_exp_f32_e32 v99, v2
	v_sub_f32_e32 v2, v83, v156
	v_exp_f32_e32 v83, v2
	v_sub_f32_e32 v2, v100, v156
	v_exp_f32_e32 v100, v2
	v_sub_f32_e32 v2, v84, v156
	v_exp_f32_e32 v84, v2
	v_sub_f32_e32 v2, v101, v156
	v_exp_f32_e32 v101, v2
	v_sub_f32_e32 v2, v85, v156
	v_exp_f32_e32 v85, v2
	v_sub_f32_e32 v2, v102, v156
	v_exp_f32_e32 v102, v2
	v_sub_f32_e32 v2, v86, v156
	v_exp_f32_e32 v86, v2
	v_sub_f32_e32 v2, v103, v156
	v_exp_f32_e32 v103, v2
	v_sub_f32_e32 v2, v87, v156
	v_exp_f32_e32 v87, v2
	v_sub_f32_e32 v2, v104, v156
	v_exp_f32_e32 v104, v2
	v_sub_f32_e32 v2, v88, v156
	v_exp_f32_e32 v88, v2
	v_sub_f32_e32 v2, v105, v156
	v_exp_f32_e32 v105, v2
	v_sub_f32_e32 v2, v89, v156
	v_exp_f32_e32 v89, v2
	v_sub_f32_e32 v2, v106, v156
	v_exp_f32_e32 v106, v2
	v_sub_f32_e32 v2, v90, v156
	v_exp_f32_e32 v90, v2
	v_sub_f32_e32 v2, v107, v156
	v_exp_f32_e32 v107, v2
	v_sub_f32_e32 v2, v91, v156
	v_exp_f32_e32 v91, v2
	v_sub_f32_e32 v2, v108, v156
	v_exp_f32_e32 v108, v2
	v_sub_f32_e32 v2, v92, v156
	v_exp_f32_e32 v92, v2
	v_sub_f32_e32 v2, v109, v156
	v_exp_f32_e32 v109, v2
	v_sub_f32_e32 v2, v93, v156
	v_exp_f32_e32 v93, v2
	v_sub_f32_e32 v2, v110, v156
	v_exp_f32_e32 v110, v2
	v_sub_f32_e32 v2, v94, v156
	v_exp_f32_e32 v94, v2
	v_sub_f32_e32 v2, v111, v156
	v_exp_f32_e32 v111, v2
	v_sub_f32_e32 v2, v95, v156
	v_exp_f32_e32 v95, v2
	v_add_f32_e32 v2, v96, v80
	v_add_f32_e32 v2, 0, v2
	v_add_f32_e32 v3, v97, v81
	v_add_f32_e32 v2, v3, v2
	v_add_f32_e32 v3, v98, v82
	v_add_f32_e32 v2, v3, v2
	v_add_f32_e32 v3, v99, v83
	v_add_f32_e32 v2, v3, v2
	v_add_f32_e32 v3, v100, v84
	v_add_f32_e32 v2, v3, v2
	v_add_f32_e32 v3, v101, v85
	v_add_f32_e32 v2, v3, v2
	v_add_f32_e32 v3, v102, v86
	v_add_f32_e32 v2, v3, v2
	v_add_f32_e32 v3, v103, v87
	v_add_f32_e32 v2, v3, v2
	v_add_f32_e32 v3, v104, v88
	v_add_f32_e32 v2, v3, v2
	v_add_f32_e32 v3, v105, v89
	v_add_f32_e32 v2, v3, v2
	v_add_f32_e32 v3, v106, v90
	v_add_f32_e32 v2, v3, v2
	v_add_f32_e32 v3, v107, v91
	v_add_f32_e32 v2, v3, v2
	v_add_f32_e32 v3, v108, v92
	v_add_f32_e32 v2, v3, v2
	v_add_f32_e32 v3, v109, v93
	v_add_f32_e32 v2, v3, v2
	v_add_f32_e32 v3, v110, v94
	v_exp_f32_e32 v0, v0
	v_add_f32_e32 v2, v3, v2
	v_add_f32_e32 v3, v111, v95
	v_add_f32_e32 v14, v3, v2
	v_mov_b32_e32 v15, v14
	v_cvt_pk_bf16_f32 v144, v96, v97
	v_cvt_pk_bf16_f32 v145, v98, v99
	v_cvt_pk_bf16_f32 v146, v100, v101
	v_cvt_pk_bf16_f32 v147, v102, v103
	v_cvt_pk_bf16_f32 v10, v104, v105
	v_cvt_pk_bf16_f32 v11, v106, v107
	v_cvt_pk_bf16_f32 v12, v108, v109
	v_cvt_pk_bf16_f32 v13, v110, v111
	v_cvt_pk_bf16_f32 v6, v80, v81
	v_cvt_pk_bf16_f32 v7, v82, v83
	v_cvt_pk_bf16_f32 v8, v84, v85
	v_cvt_pk_bf16_f32 v9, v86, v87
	v_cvt_pk_bf16_f32 v2, v88, v89
	v_cvt_pk_bf16_f32 v3, v90, v91
	v_cvt_pk_bf16_f32 v4, v92, v93
	v_cvt_pk_bf16_f32 v5, v94, v95
	s_nop 1
	v_permlane32_swap_b32_e32 v14, v15
	v_permlane32_swap_b32_e32 v144, v146
	v_permlane32_swap_b32_e32 v145, v147
	v_permlane32_swap_b32_e32 v10, v12
	v_permlane32_swap_b32_e32 v11, v13
	v_permlane32_swap_b32_e32 v6, v8
	v_permlane32_swap_b32_e32 v7, v9
	v_permlane32_swap_b32_e32 v2, v4
	v_permlane32_swap_b32_e32 v3, v5
	s_cbranch_vccnz .LBB0_866
	s_and_saveexec_b64 s[10:11], s[0:1]
	ds_write_b32 v152, v0 offset:128
	s_or_b64 exec, exec, s[10:11]
	s_waitcnt lgkmcnt(0)
	v_add_u32_e32 v163, v150, v151
	ds_read_b128 v[164:167], v163 offset:224
	ds_read_b128 v[168:171], v163 offset:192
	ds_read_b128 v[172:175], v163 offset:160
	ds_read_b128 v[180:183], v163 offset:128
	s_waitcnt lgkmcnt(0)
	v_pk_mul_f32 v[76:77], v[76:77], v[164:165]
	v_pk_mul_f32 v[72:73], v[72:73], v[168:169]
	v_pk_mul_f32 v[68:69], v[68:69], v[172:173]
	v_pk_mul_f32 v[78:79], v[78:79], v[166:167]
	v_pk_mul_f32 v[74:75], v[74:75], v[170:171]
	v_pk_mul_f32 v[70:71], v[70:71], v[174:175]
	v_pk_mul_f32 v[66:67], v[66:67], v[182:183]
	v_pk_mul_f32 v[64:65], v[64:65], v[180:181]
	v_pk_mul_f32 v[60:61], v[60:61], v[164:165]
	v_pk_mul_f32 v[56:57], v[56:57], v[168:169]
	v_pk_mul_f32 v[52:53], v[52:53], v[172:173]
	v_pk_mul_f32 v[62:63], v[62:63], v[166:167]
	v_pk_mul_f32 v[58:59], v[58:59], v[170:171]
	v_pk_mul_f32 v[54:55], v[54:55], v[174:175]
	v_pk_mul_f32 v[50:51], v[50:51], v[182:183]
	v_pk_mul_f32 v[48:49], v[48:49], v[180:181]
	v_pk_mul_f32 v[44:45], v[44:45], v[164:165]
	v_pk_mul_f32 v[40:41], v[40:41], v[168:169]
	v_pk_mul_f32 v[36:37], v[36:37], v[172:173]
	v_pk_mul_f32 v[46:47], v[46:47], v[166:167]
	v_pk_mul_f32 v[42:43], v[42:43], v[170:171]
	v_pk_mul_f32 v[38:39], v[38:39], v[174:175]
	v_pk_mul_f32 v[34:35], v[34:35], v[182:183]
	v_pk_mul_f32 v[32:33], v[32:33], v[180:181]
	v_pk_mul_f32 v[28:29], v[28:29], v[164:165]
	v_pk_mul_f32 v[24:25], v[24:25], v[168:169]
	v_pk_mul_f32 v[20:21], v[20:21], v[172:173]
	v_pk_mul_f32 v[30:31], v[30:31], v[166:167]
	v_pk_mul_f32 v[26:27], v[26:27], v[170:171]
	v_pk_mul_f32 v[22:23], v[22:23], v[174:175]
	v_pk_mul_f32 v[18:19], v[18:19], v[182:183]
	v_pk_mul_f32 v[16:17], v[16:17], v[180:181]

.LBB0_1006:
	s_or_b64 exec, exec, s[4:5]
	s_add_i32 s4, s44, 0x100
	v_cmp_le_i32_e32 vcc, s4, v182
	s_and_saveexec_b64 s[28:29], vcc
	s_cbranch_execz .LBB0_1010
	s_lshl_b32 s4, s45, 14
	s_add_i32 s4, s4, 0
	s_add_i32 s4, s4, 0x10000
	v_add3_u32 v0, s4, v185, v183
	v_add3_u32 v6, s4, v188, v183
	v_add3_u32 v7, s4, v190, v183
	v_add3_u32 v8, s4, v192, v183
	s_lshl_b32 s5, s45, 13
	s_add_i32 s5, s5, 0
	s_add_i32 s5, s5, 0x1c000
	v_add3_u32 v206, s5, v187, v184
	v_add3_u32 v207, s5, v189, v184
	v_add3_u32 v208, s5, v191, v184
	v_add3_u32 v209, s5, v193, v184
	ds_read_b128 v[216:219], v0
	ds_read_b128 v[220:223], v0 offset:8192
	ds_read_b128 v[224:227], v6
	ds_read_b128 v[228:231], v6 offset:8192
	ds_read_b128 v[232:235], v7
	ds_read_b128 v[236:239], v7 offset:8192
	ds_read_b128 v[240:243], v8
	ds_read_b128 v[244:247], v8 offset:8192
	s_waitcnt lgkmcnt(6)
	v_mfma_f32_32x32x16_bf16 v[80:95], v[216:219], v[112:115], 0
	v_mfma_f32_32x32x16_bf16 v[96:111], v[220:223], v[112:115], 0
	ds_read_b128 v[216:219], v0 offset:128
	ds_read_b128 v[220:223], v0 offset:8320
	s_waitcnt lgkmcnt(6)
	v_mfma_f32_32x32x16_bf16 v[80:95], v[224:227], v[116:119], v[80:95]
	v_mfma_f32_32x32x16_bf16 v[96:111], v[228:231], v[116:119], v[96:111]
	ds_read_b128 v[224:227], v6 offset:128
	ds_read_b128 v[228:231], v6 offset:8320
	s_waitcnt lgkmcnt(6)
	v_mfma_f32_32x32x16_bf16 v[80:95], v[232:235], v[120:123], v[80:95]
	v_mfma_f32_32x32x16_bf16 v[96:111], v[236:239], v[120:123], v[96:111]
	ds_read_b128 v[232:235], v7 offset:128
	ds_read_b128 v[236:239], v7 offset:8320
	s_waitcnt lgkmcnt(6)
	v_mfma_f32_32x32x16_bf16 v[80:95], v[240:243], v[124:127], v[80:95]
	v_mfma_f32_32x32x16_bf16 v[96:111], v[244:247], v[124:127], v[96:111]
	ds_read_b128 v[240:243], v8 offset:128
	ds_read_b128 v[244:247], v8 offset:8320
	s_waitcnt lgkmcnt(6)
	v_mfma_f32_32x32x16_bf16 v[80:95], v[216:219], v[128:131], v[80:95]
	v_mfma_f32_32x32x16_bf16 v[96:111], v[220:223], v[128:131], v[96:111]
	ds_read_b128 v[216:219], v206
	ds_read_b128 v[220:223], v206 offset:4096
	s_waitcnt lgkmcnt(6)
	v_mfma_f32_32x32x16_bf16 v[80:95], v[224:227], v[132:135], v[80:95]
	v_mfma_f32_32x32x16_bf16 v[96:111], v[228:231], v[132:135], v[96:111]
	ds_read_b128 v[224:227], v207
	ds_read_b128 v[228:231], v207 offset:4096
	s_waitcnt lgkmcnt(6)
	v_mfma_f32_32x32x16_bf16 v[80:95], v[232:235], v[136:139], v[80:95]
	v_mfma_f32_32x32x16_bf16 v[96:111], v[236:239], v[136:139], v[96:111]
	ds_read_b128 v[232:235], v208
	ds_read_b128 v[236:239], v208 offset:4096
	s_waitcnt lgkmcnt(6)
	v_mfma_f32_32x32x16_bf16 v[80:95], v[240:243], v[140:143], v[80:95]
	v_mfma_f32_32x32x16_bf16 v[96:111], v[244:247], v[140:143], v[96:111]
	ds_read_b128 v[240:243], v209
	ds_read_b128 v[244:247], v209 offset:4096
	s_add_i32 s4, s44, 0x13f
	s_waitcnt lgkmcnt(6)
	v_mfma_f32_32x32x16_bf16 v[80:95], v[216:219], v[144:147], v[80:95]
	v_mfma_f32_32x32x16_bf16 v[96:111], v[220:223], v[144:147], v[96:111]
	s_waitcnt lgkmcnt(4)
	v_mfma_f32_32x32x16_bf16 v[80:95], v[224:227], v[152:155], v[80:95]
	v_mfma_f32_32x32x16_bf16 v[96:111], v[228:231], v[152:155], v[96:111]
	s_waitcnt lgkmcnt(2)
	v_mfma_f32_32x32x16_bf16 v[80:95], v[232:235], v[148:151], v[80:95]
	v_mfma_f32_32x32x16_bf16 v[96:111], v[236:239], v[148:151], v[96:111]
	s_waitcnt lgkmcnt(0)
	v_mfma_f32_32x32x16_bf16 v[80:95], v[240:243], v[156:159], v[80:95]
	v_mfma_f32_32x32x16_bf16 v[96:111], v[244:247], v[156:159], v[96:111]
	s_nop 1
	v_cmp_gt_i32_e64 s[4:5], s4, v181
	s_and_saveexec_b64 s[30:31], s[4:5]
	s_cbranch_execz .LBB0_1009
	v_add_u32_e32 v0, s7, v194
	v_cmp_lt_i32_e64 s[4:5], -1, v0
	v_add_u32_e32 v2, -1, v0
	s_nop 2
	v_cndmask_b32_e64 v80, v214, v80, s[4:5]
	v_cmp_lt_i32_e64 s[4:5], 31, v0
	s_nop 1
	v_cndmask_b32_e64 v96, v214, v96, s[4:5]
	v_cmp_lt_i32_e64 s[4:5], -1, v2
	s_nop 1
	v_cndmask_b32_e64 v81, v214, v81, s[4:5]
	v_cmp_lt_i32_e64 s[4:5], 31, v2
	v_add_u32_e32 v2, -2, v0
	s_nop 0
	v_cndmask_b32_e64 v97, v214, v97, s[4:5]
	v_cmp_lt_i32_e64 s[4:5], -1, v2
	s_nop 1
	v_cndmask_b32_e64 v82, v214, v82, s[4:5]
	v_cmp_lt_i32_e64 s[4:5], 31, v2
	v_add_u32_e32 v2, -3, v0
	s_nop 0
	v_cndmask_b32_e64 v98, v214, v98, s[4:5]
	v_cmp_lt_i32_e64 s[4:5], -1, v2
	s_nop 1
	v_cndmask_b32_e64 v83, v214, v83, s[4:5]
	v_cmp_lt_i32_e64 s[4:5], 31, v2
	v_add_u32_e32 v2, -8, v0
	s_nop 0
	v_cndmask_b32_e64 v99, v214, v99, s[4:5]
	v_cmp_lt_i32_e64 s[4:5], -1, v2
	s_nop 1
	v_cndmask_b32_e64 v84, v214, v84, s[4:5]
	v_cmp_lt_i32_e64 s[4:5], 31, v2
	v_add_u32_e32 v2, -9, v0
	s_nop 0
	v_cndmask_b32_e64 v100, v214, v100, s[4:5]
	v_cmp_lt_i32_e64 s[4:5], -1, v2
	s_nop 1
	v_cndmask_b32_e64 v85, v214, v85, s[4:5]
	v_cmp_lt_i32_e64 s[4:5], 31, v2
	v_add_u32_e32 v2, -10, v0
	s_nop 0
	v_cndmask_b32_e64 v101, v214, v101, s[4:5]
	v_cmp_lt_i32_e64 s[4:5], -1, v2
	s_nop 1
	v_cndmask_b32_e64 v86, v214, v86, s[4:5]
	v_cmp_lt_i32_e64 s[4:5], 31, v2
	v_add_u32_e32 v2, -11, v0
	s_nop 0
	v_cndmask_b32_e64 v102, v214, v102, s[4:5]
	v_cmp_lt_i32_e64 s[4:5], -1, v2
	s_nop 1
	v_cndmask_b32_e64 v87, v214, v87, s[4:5]
	v_cmp_lt_i32_e64 s[4:5], 31, v2
	v_add_u32_e32 v2, -16, v0
	s_nop 0
	v_cndmask_b32_e64 v103, v214, v103, s[4:5]
	v_cmp_lt_i32_e64 s[4:5], -1, v2
	s_nop 1
	v_cndmask_b32_e64 v88, v214, v88, s[4:5]
	v_cmp_lt_i32_e64 s[4:5], 31, v2
	v_subrev_u32_e32 v2, 17, v0
	s_nop 0
	v_cndmask_b32_e64 v104, v214, v104, s[4:5]
	v_cmp_lt_i32_e64 s[4:5], -1, v2
	s_nop 1
	v_cndmask_b32_e64 v89, v214, v89, s[4:5]
	v_cmp_lt_i32_e64 s[4:5], 31, v2
	v_subrev_u32_e32 v2, 18, v0
	s_nop 0
	v_cndmask_b32_e64 v105, v214, v105, s[4:5]
	v_cmp_lt_i32_e64 s[4:5], -1, v2
	s_nop 1
	v_cndmask_b32_e64 v90, v214, v90, s[4:5]
	v_cmp_lt_i32_e64 s[4:5], 31, v2
	v_subrev_u32_e32 v2, 19, v0
	s_nop 0
	v_cndmask_b32_e64 v106, v214, v106, s[4:5]
	v_cmp_lt_i32_e64 s[4:5], -1, v2
	s_nop 1
	v_cndmask_b32_e64 v91, v214, v91, s[4:5]
	v_cmp_lt_i32_e64 s[4:5], 31, v2
	v_subrev_u32_e32 v2, 24, v0
	s_nop 0
	v_cndmask_b32_e64 v107, v214, v107, s[4:5]
	v_cmp_lt_i32_e64 s[4:5], -1, v2
	s_nop 1
	v_cndmask_b32_e64 v92, v214, v92, s[4:5]
	v_cmp_lt_i32_e64 s[4:5], 31, v2
	v_subrev_u32_e32 v2, 25, v0
	s_nop 0
	v_cndmask_b32_e64 v108, v214, v108, s[4:5]
	v_cmp_lt_i32_e64 s[4:5], -1, v2
	s_nop 1
	v_cndmask_b32_e64 v93, v214, v93, s[4:5]
	v_cmp_lt_i32_e64 s[4:5], 31, v2
	v_subrev_u32_e32 v2, 26, v0
	v_subrev_u32_e32 v0, 27, v0
	v_cndmask_b32_e64 v109, v214, v109, s[4:5]
	v_cmp_lt_i32_e64 s[4:5], -1, v2
	s_nop 1
	v_cndmask_b32_e64 v94, v214, v94, s[4:5]
	v_cmp_lt_i32_e64 s[4:5], 31, v2
	s_nop 1
	v_cndmask_b32_e64 v110, v214, v110, s[4:5]
	v_cmp_lt_i32_e64 s[4:5], -1, v0
	s_nop 1
	v_cndmask_b32_e64 v95, v214, v95, s[4:5]
	v_cmp_lt_i32_e64 s[4:5], 31, v0
	s_nop 1
	v_cndmask_b32_e64 v111, v214, v111, s[4:5]

.LBB0_1048:
	s_or_b64 exec, exec, s[6:7]
	s_cmp_ge_u32 s29, s35
	s_cselect_b64 s[20:21], -1, 0
	s_mov_b64 s[6:7], 0
	s_and_b64 vcc, exec, s[20:21]
	s_cbranch_vccnz .LBB0_1056
	s_add_i32 s26, s36, 63
	v_cmp_le_i32_e32 vcc, s36, v185
	v_cmp_ge_i32_e64 s[6:7], s26, v199
	s_and_b64 s[40:41], vcc, s[6:7]
	s_mov_b64 s[6:7], 0
	s_and_saveexec_b64 s[24:25], s[40:41]
	s_cbranch_execz .LBB0_1053
	s_lshl_b32 s6, s37, 14
	s_add_i32 s6, s6, 0
	s_add_i32 s6, s6, 0x10000
	v_add3_u32 v0, s6, v192, v190
	v_add3_u32 v6, s6, v193, v190
	v_add3_u32 v7, s6, v194, v190
	v_add3_u32 v8, s6, v195, v190
	ds_read_b128 v[220:223], v0
	ds_read_b128 v[224:227], v0 offset:8192
	ds_read_b128 v[228:231], v6
	ds_read_b128 v[232:235], v6 offset:8192
	ds_read_b128 v[236:239], v7
	ds_read_b128 v[240:243], v7 offset:8192
	ds_read_b128 v[244:247], v8
	ds_read_b128 v[208:211], v8 offset:8192
	s_waitcnt lgkmcnt(6)
	v_mfma_f32_32x32x16_bf16 v[80:95], v[220:223], v[112:115], 0
	v_mfma_f32_32x32x16_bf16 v[96:111], v[224:227], v[112:115], 0
	ds_read_b128 v[220:223], v0 offset:128
	ds_read_b128 v[224:227], v0 offset:8320
	s_waitcnt lgkmcnt(6)
	v_mfma_f32_32x32x16_bf16 v[80:95], v[228:231], v[120:123], v[80:95]
	v_mfma_f32_32x32x16_bf16 v[96:111], v[232:235], v[120:123], v[96:111]
	ds_read_b128 v[228:231], v6 offset:128
	ds_read_b128 v[232:235], v6 offset:8320
	s_waitcnt lgkmcnt(6)
	v_mfma_f32_32x32x16_bf16 v[80:95], v[236:239], v[128:131], v[80:95]
	v_mfma_f32_32x32x16_bf16 v[96:111], v[240:243], v[128:131], v[96:111]
	ds_read_b128 v[236:239], v7 offset:128
	ds_read_b128 v[240:243], v7 offset:8320
	s_waitcnt lgkmcnt(6)
	v_mfma_f32_32x32x16_bf16 v[80:95], v[244:247], v[136:139], v[80:95]
	v_mfma_f32_32x32x16_bf16 v[96:111], v[208:211], v[136:139], v[96:111]
	ds_read_b128 v[244:247], v8 offset:128
	ds_read_b128 v[208:211], v8 offset:8320
	v_cmp_gt_i32_e32 vcc, s26, v183
	v_cmp_lt_i32_e64 s[6:7], s36, v200
	s_or_b64 s[26:27], vcc, s[6:7]
	s_waitcnt lgkmcnt(6)
	v_mfma_f32_32x32x16_bf16 v[80:95], v[220:223], v[116:119], v[80:95]
	v_mfma_f32_32x32x16_bf16 v[96:111], v[224:227], v[116:119], v[96:111]
	s_waitcnt lgkmcnt(4)
	v_mfma_f32_32x32x16_bf16 v[80:95], v[228:231], v[124:127], v[80:95]
	v_mfma_f32_32x32x16_bf16 v[96:111], v[232:235], v[124:127], v[96:111]
	s_waitcnt lgkmcnt(2)
	v_mfma_f32_32x32x16_bf16 v[80:95], v[236:239], v[132:135], v[80:95]
	v_mfma_f32_32x32x16_bf16 v[96:111], v[240:243], v[132:135], v[96:111]
	s_waitcnt lgkmcnt(0)
	v_mfma_f32_32x32x16_bf16 v[80:95], v[244:247], v[140:143], v[80:95]
	v_mfma_f32_32x32x16_bf16 v[96:111], v[208:211], v[140:143], v[96:111]
	s_nop 1
	s_and_saveexec_b64 s[6:7], s[26:27]
	s_cbranch_execz .LBB0_1052
	s_movk_i32 s26, 0x81
	v_subrev_u32_e32 v0, 32, v216
	v_cmp_gt_u32_e32 vcc, s26, v216
	v_subrev_u32_e32 v2, 33, v216
	s_nop 2
	v_cndmask_b32_e32 v80, v214, v80, vcc
	v_cmp_gt_u32_e32 vcc, s26, v0
	v_add_u32_e32 v0, -1, v216
	s_nop 0
	v_cndmask_b32_e32 v96, v214, v96, vcc
	v_cmp_gt_u32_e32 vcc, s26, v0
	v_add_u32_e32 v0, -2, v216
	s_nop 0
	v_cndmask_b32_e32 v81, v214, v81, vcc
	v_cmp_gt_u32_e32 vcc, s26, v2
	v_subrev_u32_e32 v2, 34, v216
	s_nop 0
	v_cndmask_b32_e32 v97, v214, v97, vcc
	v_cmp_gt_u32_e32 vcc, s26, v0
	v_add_u32_e32 v0, -3, v216
	s_nop 0
	v_cndmask_b32_e32 v82, v214, v82, vcc
	v_cmp_gt_u32_e32 vcc, s26, v2
	v_subrev_u32_e32 v2, 35, v216
	s_nop 0
	v_cndmask_b32_e32 v98, v214, v98, vcc
	v_cmp_gt_u32_e32 vcc, s26, v0
	v_add_u32_e32 v0, -8, v216
	s_nop 0
	v_cndmask_b32_e32 v83, v214, v83, vcc
	v_cmp_gt_u32_e32 vcc, s26, v2
	v_subrev_u32_e32 v2, 40, v216
	s_nop 0
	v_cndmask_b32_e32 v99, v214, v99, vcc
	v_cmp_gt_u32_e32 vcc, s26, v0
	v_add_u32_e32 v0, -9, v216
	s_nop 0
	v_cndmask_b32_e32 v84, v214, v84, vcc
	v_cmp_gt_u32_e32 vcc, s26, v2
	v_subrev_u32_e32 v2, 41, v216
	s_nop 0
	v_cndmask_b32_e32 v100, v214, v100, vcc
	v_cmp_gt_u32_e32 vcc, s26, v0
	v_add_u32_e32 v0, -10, v216
	s_nop 0
	v_cndmask_b32_e32 v85, v214, v85, vcc
	v_cmp_gt_u32_e32 vcc, s26, v2
	v_subrev_u32_e32 v2, 42, v216
	s_nop 0
	v_cndmask_b32_e32 v101, v214, v101, vcc
	v_cmp_gt_u32_e32 vcc, s26, v0
	v_add_u32_e32 v0, -11, v216
	s_nop 0
	v_cndmask_b32_e32 v86, v214, v86, vcc
	v_cmp_gt_u32_e32 vcc, s26, v2
	v_subrev_u32_e32 v2, 43, v216
	s_nop 0
	v_cndmask_b32_e32 v102, v214, v102, vcc
	v_cmp_gt_u32_e32 vcc, s26, v0
	v_add_u32_e32 v0, -16, v216
	s_nop 0
	v_cndmask_b32_e32 v87, v214, v87, vcc
	v_cmp_gt_u32_e32 vcc, s26, v2
	v_subrev_u32_e32 v2, 48, v216
	s_nop 0
	v_cndmask_b32_e32 v103, v214, v103, vcc
	v_cmp_gt_u32_e32 vcc, s26, v0
	v_subrev_u32_e32 v0, 17, v216
	s_nop 0
	v_cndmask_b32_e32 v88, v214, v88, vcc
	v_cmp_gt_u32_e32 vcc, s26, v2
	v_subrev_u32_e32 v2, 49, v216
	s_nop 0
	v_cndmask_b32_e32 v104, v214, v104, vcc
	v_cmp_gt_u32_e32 vcc, s26, v0
	v_subrev_u32_e32 v0, 18, v216
	s_nop 0
	v_cndmask_b32_e32 v89, v214, v89, vcc
	v_cmp_gt_u32_e32 vcc, s26, v2
	v_subrev_u32_e32 v2, 50, v216
	s_nop 0
	v_cndmask_b32_e32 v105, v214, v105, vcc
	v_cmp_gt_u32_e32 vcc, s26, v0
	v_subrev_u32_e32 v0, 19, v216
	s_nop 0
	v_cndmask_b32_e32 v90, v214, v90, vcc
	v_cmp_gt_u32_e32 vcc, s26, v2
	v_subrev_u32_e32 v2, 51, v216
	s_nop 0
	v_cndmask_b32_e32 v106, v214, v106, vcc
	v_cmp_gt_u32_e32 vcc, s26, v0
	v_subrev_u32_e32 v0, 24, v216
	s_nop 0
	v_cndmask_b32_e32 v91, v214, v91, vcc
	v_cmp_gt_u32_e32 vcc, s26, v2
	v_subrev_u32_e32 v2, 56, v216
	s_nop 0
	v_cndmask_b32_e32 v107, v214, v107, vcc
	v_cmp_gt_u32_e32 vcc, s26, v0
	v_subrev_u32_e32 v0, 25, v216
	s_nop 0
	v_cndmask_b32_e32 v92, v214, v92, vcc
	v_cmp_gt_u32_e32 vcc, s26, v2
	v_subrev_u32_e32 v2, 57, v216
	s_nop 0
	v_cndmask_b32_e32 v108, v214, v108, vcc
	v_cmp_gt_u32_e32 vcc, s26, v0
	v_subrev_u32_e32 v0, 26, v216
	s_nop 0
	v_cndmask_b32_e32 v93, v214, v93, vcc
	v_cmp_gt_u32_e32 vcc, s26, v2
	v_subrev_u32_e32 v2, 58, v216
	s_nop 0
	v_cndmask_b32_e32 v109, v214, v109, vcc
	v_cmp_gt_u32_e32 vcc, s26, v0
	v_subrev_u32_e32 v0, 27, v216
	s_nop 0
	v_cndmask_b32_e32 v94, v214, v94, vcc
	v_cmp_gt_u32_e32 vcc, s26, v2
	v_subrev_u32_e32 v2, 59, v216
	s_nop 0
	v_cndmask_b32_e32 v110, v214, v110, vcc
	v_cmp_gt_u32_e32 vcc, s26, v0
	s_nop 1
	v_cndmask_b32_e32 v95, v214, v95, vcc
	v_cmp_gt_u32_e32 vcc, s26, v2
	s_nop 1
	v_cndmask_b32_e32 v111, v214, v111, vcc

.LBB0_1083:
	s_or_b64 exec, exec, s[20:21]
	s_cmp_lt_u32 s43, s37
	s_cselect_b64 s[20:21], -1, 0
	v_cmp_le_i32_e32 vcc, s39, v159
	s_and_b64 s[20:21], s[20:21], vcc
	s_and_saveexec_b64 s[24:25], s[20:21]
	s_cbranch_execz .LBB0_1087
	s_lshl_b32 s26, s41, 14
	s_add_i32 s26, s26, 0
	s_add_i32 s26, s26, 0x10000
	v_add3_u32 v0, s26, v168, v166
	v_add3_u32 v6, s26, v169, v166
	v_add3_u32 v7, s26, v170, v166
	v_add3_u32 v8, s26, v171, v166
	ds_read_b128 v[216:219], v0
	ds_read_b128 v[220:223], v0 offset:8192
	ds_read_b128 v[224:227], v6
	ds_read_b128 v[228:231], v6 offset:8192
	ds_read_b128 v[232:235], v7
	ds_read_b128 v[236:239], v7 offset:8192
	ds_read_b128 v[240:243], v8
	ds_read_b128 v[244:247], v8 offset:8192
	s_waitcnt lgkmcnt(6)
	v_mfma_f32_32x32x16_bf16 v[80:95], v[216:219], v[112:115], 0
	v_mfma_f32_32x32x16_bf16 v[96:111], v[220:223], v[112:115], 0
	ds_read_b128 v[216:219], v0 offset:128
	ds_read_b128 v[220:223], v0 offset:8320
	s_waitcnt lgkmcnt(6)
	v_mfma_f32_32x32x16_bf16 v[80:95], v[224:227], v[120:123], v[80:95]
	v_mfma_f32_32x32x16_bf16 v[96:111], v[228:231], v[120:123], v[96:111]
	ds_read_b128 v[224:227], v6 offset:128
	ds_read_b128 v[228:231], v6 offset:8320
	s_waitcnt lgkmcnt(6)
	v_mfma_f32_32x32x16_bf16 v[80:95], v[232:235], v[128:131], v[80:95]
	v_mfma_f32_32x32x16_bf16 v[96:111], v[236:239], v[128:131], v[96:111]
	ds_read_b128 v[232:235], v7 offset:128
	ds_read_b128 v[236:239], v7 offset:8320
	s_waitcnt lgkmcnt(6)
	v_mfma_f32_32x32x16_bf16 v[80:95], v[240:243], v[136:139], v[80:95]
	v_mfma_f32_32x32x16_bf16 v[96:111], v[244:247], v[136:139], v[96:111]
	ds_read_b128 v[240:243], v8 offset:128
	ds_read_b128 v[244:247], v8 offset:8320
	v_lshrrev_b32_e32 v0, v174, v144
	v_lshrrev_b32_e32 v6, v174, v145
	v_bfe_i32 v7, v0, 0, 1
	v_bfe_i32 v8, v6, 0, 1
	s_waitcnt lgkmcnt(6)
	v_mfma_f32_32x32x16_bf16 v[80:95], v[216:219], v[116:119], v[80:95]
	v_mfma_f32_32x32x16_bf16 v[96:111], v[220:223], v[116:119], v[96:111]
	s_waitcnt lgkmcnt(4)
	v_mfma_f32_32x32x16_bf16 v[80:95], v[224:227], v[124:127], v[80:95]
	v_mfma_f32_32x32x16_bf16 v[96:111], v[228:231], v[124:127], v[96:111]
	s_waitcnt lgkmcnt(2)
	v_mfma_f32_32x32x16_bf16 v[80:95], v[232:235], v[132:135], v[80:95]
	v_mfma_f32_32x32x16_bf16 v[96:111], v[236:239], v[132:135], v[96:111]
	s_waitcnt lgkmcnt(0)
	v_mfma_f32_32x32x16_bf16 v[80:95], v[240:243], v[140:143], v[80:95]
	v_mfma_f32_32x32x16_bf16 v[96:111], v[244:247], v[140:143], v[96:111]
	s_nop 2
	v_bfe_i32 v2, v0, 1, 1
	v_bfe_i32 v3, v6, 1, 1
	s_nop 5
	v_bitop3_b32 v81, v81, s87, v2 bitop3:0xe4
	v_bfe_i32 v2, v0, 2, 1
	v_bitop3_b32 v82, v82, s87, v2 bitop3:0xe4
	v_bfe_i32 v2, v0, 3, 1
	v_bitop3_b32 v83, v83, s87, v2 bitop3:0xe4
	v_bitop3_b32 v97, v97, s87, v3 bitop3:0xe4
	v_bfe_i32 v3, v6, 2, 1
	v_bitop3_b32 v98, v98, s87, v3 bitop3:0xe4
	v_bfe_i32 v3, v6, 3, 1
	v_bfe_i32 v2, v0, 8, 1
	v_bitop3_b32 v99, v99, s87, v3 bitop3:0xe4
	v_bfe_i32 v3, v6, 8, 1
	v_bitop3_b32 v84, v84, s87, v2 bitop3:0xe4
	v_bfe_i32 v2, v0, 9, 1
	v_bitop3_b32 v100, v100, s87, v3 bitop3:0xe4
	v_bfe_i32 v3, v6, 9, 1
	v_bitop3_b32 v85, v85, s87, v2 bitop3:0xe4
	v_bfe_i32 v2, v0, 10, 1
	v_bitop3_b32 v101, v101, s87, v3 bitop3:0xe4
	v_bfe_i32 v3, v6, 10, 1
	v_bitop3_b32 v86, v86, s87, v2 bitop3:0xe4
	v_bfe_i32 v2, v0, 11, 1
	v_bitop3_b32 v102, v102, s87, v3 bitop3:0xe4
	v_bfe_i32 v3, v6, 11, 1
	v_bitop3_b32 v87, v87, s87, v2 bitop3:0xe4
	v_bfe_i32 v2, v0, 16, 1
	v_bitop3_b32 v103, v103, s87, v3 bitop3:0xe4
	v_bfe_i32 v3, v6, 16, 1
	v_bitop3_b32 v88, v88, s87, v2 bitop3:0xe4
	v_bfe_i32 v2, v0, 17, 1
	v_bitop3_b32 v104, v104, s87, v3 bitop3:0xe4
	v_bfe_i32 v3, v6, 17, 1
	v_bitop3_b32 v89, v89, s87, v2 bitop3:0xe4
	v_bfe_i32 v2, v0, 18, 1
	v_bitop3_b32 v105, v105, s87, v3 bitop3:0xe4
	v_bfe_i32 v3, v6, 18, 1
	v_bitop3_b32 v90, v90, s87, v2 bitop3:0xe4
	v_bfe_i32 v2, v0, 19, 1
	v_bitop3_b32 v106, v106, s87, v3 bitop3:0xe4
	v_bfe_i32 v3, v6, 19, 1
	v_bitop3_b32 v91, v91, s87, v2 bitop3:0xe4
	v_bfe_i32 v2, v0, 24, 1
	v_bitop3_b32 v107, v107, s87, v3 bitop3:0xe4
	v_bfe_i32 v3, v6, 24, 1
	v_bitop3_b32 v92, v92, s87, v2 bitop3:0xe4
	v_bfe_i32 v2, v0, 25, 1
	v_bitop3_b32 v108, v108, s87, v3 bitop3:0xe4
	v_bfe_i32 v3, v6, 25, 1
	v_bitop3_b32 v93, v93, s87, v2 bitop3:0xe4
	v_bfe_i32 v2, v0, 26, 1
	v_bitop3_b32 v109, v109, s87, v3 bitop3:0xe4
	v_bfe_i32 v3, v6, 26, 1
	v_bitop3_b32 v94, v94, s87, v2 bitop3:0xe4
	v_bfe_i32 v0, v0, 27, 1
	v_bfe_i32 v2, v6, 27, 1
	v_bitop3_b32 v80, v80, s87, v7 bitop3:0xe4
	v_bitop3_b32 v96, v96, s87, v8 bitop3:0xe4
	v_bitop3_b32 v110, v110, s87, v3 bitop3:0xe4
	v_bitop3_b32 v95, v95, s87, v0 bitop3:0xe4
	v_bitop3_b32 v111, v111, s87, v2 bitop3:0xe4
	s_or_b64 exec, exec, s[24:25]
	s_and_b64 s[26:27], s[20:21], s[16:17]
	s_and_saveexec_b64 s[24:25], s[26:27]
	s_cbranch_execnz .LBB0_1088

.LBB0_1138:
	s_or_b64 exec, exec, s[20:21]
	s_add_i32 s20, s59, 0x100
	v_cmp_le_i32_e32 vcc, s20, v171
	s_and_saveexec_b64 s[44:45], vcc
	s_cbranch_execz .LBB0_1142
	s_lshl_b32 s20, s60, 14
	s_add_i32 s20, s20, 0
	s_add_i32 s20, s20, 0x10000
	v_add3_u32 v0, s20, v174, v172
	v_add3_u32 v6, s20, v175, v172
	v_add3_u32 v7, s20, v176, v172
	v_add3_u32 v8, s20, v177, v172
	ds_read_b128 v[80:83], v179
	ds_read_b128 v[84:87], v179 offset:32
	ds_read_b128 v[88:91], v179 offset:64
	ds_read_b128 v[92:95], v179 offset:96
	ds_read_b128 v[96:99], v179 offset:128
	ds_read_b128 v[100:103], v179 offset:160
	ds_read_b128 v[104:107], v179 offset:192
	ds_read_b128 v[108:111], v179 offset:224
	ds_read_b128 v[216:219], v0
	ds_read_b128 v[220:223], v0 offset:8192
	ds_read_b128 v[224:227], v6
	ds_read_b128 v[228:231], v6 offset:8192
	ds_read_b128 v[232:235], v7
	ds_read_b128 v[236:239], v7 offset:8192
	s_waitcnt lgkmcnt(4)
	v_mfma_f32_32x32x16_bf16 v[80:95], v[216:219], v[112:115], v[80:95]
	v_mfma_f32_32x32x16_bf16 v[96:111], v[220:223], v[112:115], v[96:111]
	ds_read_b128 v[216:219], v8
	ds_read_b128 v[220:223], v8 offset:8192
	s_waitcnt lgkmcnt(4)
	v_mfma_f32_32x32x16_bf16 v[80:95], v[224:227], v[116:119], v[80:95]
	v_mfma_f32_32x32x16_bf16 v[96:111], v[228:231], v[116:119], v[96:111]
	ds_read_b128 v[224:227], v0 offset:128
	ds_read_b128 v[228:231], v0 offset:8320
	s_waitcnt lgkmcnt(4)
	v_mfma_f32_32x32x16_bf16 v[80:95], v[232:235], v[120:123], v[80:95]
	v_mfma_f32_32x32x16_bf16 v[96:111], v[236:239], v[120:123], v[96:111]
	ds_read_b128 v[232:235], v6 offset:128
	ds_read_b128 v[236:239], v6 offset:8320
	s_waitcnt lgkmcnt(4)
	v_mfma_f32_32x32x16_bf16 v[80:95], v[216:219], v[124:127], v[80:95]
	v_mfma_f32_32x32x16_bf16 v[96:111], v[220:223], v[124:127], v[96:111]
	ds_read_b128 v[216:219], v7 offset:128
	ds_read_b128 v[220:223], v7 offset:8320
	s_waitcnt lgkmcnt(4)
	v_mfma_f32_32x32x16_bf16 v[80:95], v[224:227], v[128:131], v[80:95]
	v_mfma_f32_32x32x16_bf16 v[96:111], v[228:231], v[128:131], v[96:111]
	ds_read_b128 v[224:227], v8 offset:128
	ds_read_b128 v[228:231], v8 offset:8320
	s_add_i32 s20, s59, 0x13f
	v_cmp_gt_i32_e64 s[20:21], s20, v170
	s_waitcnt lgkmcnt(4)
	v_mfma_f32_32x32x16_bf16 v[80:95], v[232:235], v[132:135], v[80:95]
	v_mfma_f32_32x32x16_bf16 v[96:111], v[236:239], v[132:135], v[96:111]
	s_waitcnt lgkmcnt(2)
	v_mfma_f32_32x32x16_bf16 v[80:95], v[216:219], v[136:139], v[80:95]
	v_mfma_f32_32x32x16_bf16 v[96:111], v[220:223], v[136:139], v[96:111]
	s_waitcnt lgkmcnt(0)
	v_mfma_f32_32x32x16_bf16 v[80:95], v[224:227], v[140:143], v[80:95]
	v_mfma_f32_32x32x16_bf16 v[96:111], v[228:231], v[140:143], v[96:111]
	s_nop 1
	s_and_saveexec_b64 s[46:47], s[20:21]
	s_cbranch_execz .LBB0_1141
	v_add_u32_e32 v0, s52, v180
	v_cmp_lt_i32_e64 s[20:21], -1, v0
	v_add_u32_e32 v2, -1, v0
	s_nop 3
	v_cndmask_b32_e64 v80, v214, v80, s[20:21]
	v_cmp_lt_i32_e64 s[20:21], 31, v0
	s_nop 1
	v_cndmask_b32_e64 v96, v214, v96, s[20:21]
	v_cmp_lt_i32_e64 s[20:21], -1, v2
	s_nop 1
	v_cndmask_b32_e64 v81, v214, v81, s[20:21]
	v_cmp_lt_i32_e64 s[20:21], 31, v2
	v_add_u32_e32 v2, -2, v0
	s_nop 0
	v_cndmask_b32_e64 v97, v214, v97, s[20:21]
	v_cmp_lt_i32_e64 s[20:21], -1, v2
	s_nop 1
	v_cndmask_b32_e64 v82, v214, v82, s[20:21]
	v_cmp_lt_i32_e64 s[20:21], 31, v2
	v_add_u32_e32 v2, -3, v0
	s_nop 0
	v_cndmask_b32_e64 v98, v214, v98, s[20:21]
	v_cmp_lt_i32_e64 s[20:21], -1, v2
	s_nop 1
	v_cndmask_b32_e64 v83, v214, v83, s[20:21]
	v_cmp_lt_i32_e64 s[20:21], 31, v2
	v_add_u32_e32 v2, -8, v0
	s_nop 0
	v_cndmask_b32_e64 v99, v214, v99, s[20:21]
	v_cmp_lt_i32_e64 s[20:21], -1, v2
	s_nop 1
	v_cndmask_b32_e64 v84, v214, v84, s[20:21]
	v_cmp_lt_i32_e64 s[20:21], 31, v2
	v_add_u32_e32 v2, -9, v0
	s_nop 0
	v_cndmask_b32_e64 v100, v214, v100, s[20:21]
	v_cmp_lt_i32_e64 s[20:21], -1, v2
	s_nop 1
	v_cndmask_b32_e64 v85, v214, v85, s[20:21]
	v_cmp_lt_i32_e64 s[20:21], 31, v2
	v_add_u32_e32 v2, -10, v0
	s_nop 0
	v_cndmask_b32_e64 v101, v214, v101, s[20:21]
	v_cmp_lt_i32_e64 s[20:21], -1, v2
	s_nop 1
	v_cndmask_b32_e64 v86, v214, v86, s[20:21]
	v_cmp_lt_i32_e64 s[20:21], 31, v2
	v_add_u32_e32 v2, -11, v0
	s_nop 0
	v_cndmask_b32_e64 v102, v214, v102, s[20:21]
	v_cmp_lt_i32_e64 s[20:21], -1, v2
	s_nop 1
	v_cndmask_b32_e64 v87, v214, v87, s[20:21]
	v_cmp_lt_i32_e64 s[20:21], 31, v2
	v_add_u32_e32 v2, -16, v0
	s_nop 0
	v_cndmask_b32_e64 v103, v214, v103, s[20:21]
	v_cmp_lt_i32_e64 s[20:21], -1, v2
	s_nop 1
	v_cndmask_b32_e64 v88, v214, v88, s[20:21]
	v_cmp_lt_i32_e64 s[20:21], 31, v2
	v_subrev_u32_e32 v2, 17, v0
	s_nop 0
	v_cndmask_b32_e64 v104, v214, v104, s[20:21]
	v_cmp_lt_i32_e64 s[20:21], -1, v2
	s_nop 1
	v_cndmask_b32_e64 v89, v214, v89, s[20:21]
	v_cmp_lt_i32_e64 s[20:21], 31, v2
	v_subrev_u32_e32 v2, 18, v0
	s_nop 0
	v_cndmask_b32_e64 v105, v214, v105, s[20:21]
	v_cmp_lt_i32_e64 s[20:21], -1, v2
	s_nop 1
	v_cndmask_b32_e64 v90, v214, v90, s[20:21]
	v_cmp_lt_i32_e64 s[20:21], 31, v2
	v_subrev_u32_e32 v2, 19, v0
	s_nop 0
	v_cndmask_b32_e64 v106, v214, v106, s[20:21]
	v_cmp_lt_i32_e64 s[20:21], -1, v2
	s_nop 1
	v_cndmask_b32_e64 v91, v214, v91, s[20:21]
	v_cmp_lt_i32_e64 s[20:21], 31, v2
	v_subrev_u32_e32 v2, 24, v0
	s_nop 0
	v_cndmask_b32_e64 v107, v214, v107, s[20:21]
	v_cmp_lt_i32_e64 s[20:21], -1, v2
	s_nop 1
	v_cndmask_b32_e64 v92, v214, v92, s[20:21]
	v_cmp_lt_i32_e64 s[20:21], 31, v2
	v_subrev_u32_e32 v2, 25, v0
	s_nop 0
	v_cndmask_b32_e64 v108, v214, v108, s[20:21]
	v_cmp_lt_i32_e64 s[20:21], -1, v2
	s_nop 1
	v_cndmask_b32_e64 v93, v214, v93, s[20:21]
	v_cmp_lt_i32_e64 s[20:21], 31, v2
	v_subrev_u32_e32 v2, 26, v0
	v_subrev_u32_e32 v0, 27, v0
	v_cndmask_b32_e64 v109, v214, v109, s[20:21]
	v_cmp_lt_i32_e64 s[20:21], -1, v2
	s_nop 1
	v_cndmask_b32_e64 v94, v214, v94, s[20:21]
	v_cmp_lt_i32_e64 s[20:21], 31, v2
	s_nop 1
	v_cndmask_b32_e64 v110, v214, v110, s[20:21]
	v_cmp_lt_i32_e64 s[20:21], -1, v0
	s_nop 1
	v_cndmask_b32_e64 v95, v214, v95, s[20:21]
	v_cmp_lt_i32_e64 s[20:21], 31, v0
	s_nop 1
	v_cndmask_b32_e64 v111, v214, v111, s[20:21]

.LBB0_1172:
	s_lshl_b32 s14, s34, 14
	s_add_i32 s14, s14, 0
	s_add_i32 s14, s14, 0x10000
	v_add3_u32 v0, s14, v157, v156
	v_add3_u32 v6, s14, v159, v156
	v_add3_u32 v7, s14, v160, v156
	v_add3_u32 v8, s14, v161, v156
	ds_read_b128 v[216:219], v0
	ds_read_b128 v[220:223], v0 offset:8192
	ds_read_b128 v[224:227], v6
	ds_read_b128 v[228:231], v6 offset:8192
	ds_read_b128 v[232:235], v7
	ds_read_b128 v[236:239], v7 offset:8192
	ds_read_b128 v[240:243], v8
	ds_read_b128 v[244:247], v8 offset:8192
	s_waitcnt lgkmcnt(6)
	v_mfma_f32_32x32x16_bf16 v[96:111], v[216:219], v[112:115], 0
	v_mfma_f32_32x32x16_bf16 v[80:95], v[220:223], v[112:115], 0
	ds_read_b128 v[216:219], v0 offset:128
	ds_read_b128 v[220:223], v0 offset:8320
	s_waitcnt lgkmcnt(6)
	v_mfma_f32_32x32x16_bf16 v[96:111], v[224:227], v[116:119], v[96:111]
	v_mfma_f32_32x32x16_bf16 v[80:95], v[228:231], v[116:119], v[80:95]
	ds_read_b128 v[224:227], v6 offset:128
	ds_read_b128 v[228:231], v6 offset:8320
	s_waitcnt lgkmcnt(6)
	v_mfma_f32_32x32x16_bf16 v[96:111], v[232:235], v[120:123], v[96:111]
	v_mfma_f32_32x32x16_bf16 v[80:95], v[236:239], v[120:123], v[80:95]
	ds_read_b128 v[232:235], v7 offset:128
	ds_read_b128 v[236:239], v7 offset:8320
	s_waitcnt lgkmcnt(6)
	v_mfma_f32_32x32x16_bf16 v[96:111], v[240:243], v[124:127], v[96:111]
	v_mfma_f32_32x32x16_bf16 v[80:95], v[244:247], v[124:127], v[80:95]
	ds_read_b128 v[240:243], v8 offset:128
	ds_read_b128 v[244:247], v8 offset:8320
	s_andn2_b64 vcc, exec, s[10:11]
	s_waitcnt lgkmcnt(6)
	v_mfma_f32_32x32x16_bf16 v[96:111], v[216:219], v[128:131], v[96:111]
	v_mfma_f32_32x32x16_bf16 v[80:95], v[220:223], v[128:131], v[80:95]
	s_waitcnt lgkmcnt(4)
	v_mfma_f32_32x32x16_bf16 v[96:111], v[224:227], v[132:135], v[96:111]
	v_mfma_f32_32x32x16_bf16 v[80:95], v[228:231], v[132:135], v[80:95]
	s_waitcnt lgkmcnt(2)
	v_mfma_f32_32x32x16_bf16 v[96:111], v[232:235], v[136:139], v[96:111]
	v_mfma_f32_32x32x16_bf16 v[80:95], v[236:239], v[136:139], v[80:95]
	s_waitcnt lgkmcnt(0)
	v_mfma_f32_32x32x16_bf16 v[96:111], v[240:243], v[140:143], v[96:111]
	v_mfma_f32_32x32x16_bf16 v[80:95], v[244:247], v[140:143], v[80:95]
	s_nop 1
	s_cbranch_vccnz .LBB0_1182
	s_nop 7
	v_max_f32_e32 v0, v97, v97
	v_max_f32_e32 v2, v96, v96
	v_max_f32_e32 v0, v2, v0
	v_max3_f32 v0, v0, v98, v99
	v_max3_f32 v0, v0, v100, v101
	v_max3_f32 v0, v0, v102, v103
	v_max3_f32 v0, v0, v104, v105
	v_max3_f32 v0, v0, v106, v107
	v_max3_f32 v0, v0, v108, v109
	v_max3_f32 v0, v0, v110, v111
	v_max3_f32 v0, v0, v80, v81
	v_max3_f32 v0, v0, v82, v83
	v_max3_f32 v0, v0, v84, v85
	v_max3_f32 v0, v0, v86, v87
	v_max3_f32 v0, v0, v88, v89
	v_max3_f32 v0, v0, v90, v91
	v_max3_f32 v0, v0, v92, v93
	v_max3_f32 v0, v0, v94, v95
	v_mov_b32_e32 v2, v0
	s_nop 1
	v_permlane32_swap_b32_e32 v0, v2
	v_max_f32_e32 v2, v2, v2
	v_max_f32_e32 v0, v0, v0
	v_max_f32_e32 v0, v0, v2
	v_sub_f32_e32 v2, v0, v158
	v_cmp_ge_f32_e32 vcc, s86, v2
	s_cmp_eq_u64 vcc, exec
	v_max_f32_e32 v2, v158, v158
	v_max_f32_e32 v2, v2, v0
	s_cselect_b64 vcc, -1, 0
	v_sub_f32_e32 v0, v158, v2
	v_cndmask_b32_e32 v158, v2, v158, vcc
	v_sub_f32_e32 v2, v96, v158
	v_exp_f32_e32 v96, v2
	v_sub_f32_e32 v2, v80, v158
	v_exp_f32_e32 v80, v2
	v_sub_f32_e32 v2, v97, v158
	v_exp_f32_e32 v97, v2
	v_sub_f32_e32 v2, v81, v158
	v_exp_f32_e32 v81, v2
	v_sub_f32_e32 v2, v98, v158
	v_exp_f32_e32 v98, v2
	v_sub_f32_e32 v2, v82, v158
	v_exp_f32_e32 v82, v2
	v_sub_f32_e32 v2, v99, v158
	v_exp_f32_e32 v99, v2
	v_sub_f32_e32 v2, v83, v158
	v_exp_f32_e32 v83, v2
	v_sub_f32_e32 v2, v100, v158
	v_exp_f32_e32 v100, v2
	v_sub_f32_e32 v2, v84, v158
	v_exp_f32_e32 v84, v2
	v_sub_f32_e32 v2, v101, v158
	v_exp_f32_e32 v101, v2
	v_sub_f32_e32 v2, v85, v158
	v_exp_f32_e32 v85, v2
	v_sub_f32_e32 v2, v102, v158
	v_exp_f32_e32 v102, v2
	v_sub_f32_e32 v2, v86, v158
	v_exp_f32_e32 v86, v2
	v_sub_f32_e32 v2, v103, v158
	v_exp_f32_e32 v103, v2
	v_sub_f32_e32 v2, v87, v158
	v_exp_f32_e32 v87, v2
	v_sub_f32_e32 v2, v104, v158
	v_exp_f32_e32 v104, v2
	v_sub_f32_e32 v2, v88, v158
	v_exp_f32_e32 v88, v2
	v_sub_f32_e32 v2, v105, v158
	v_exp_f32_e32 v105, v2
	v_sub_f32_e32 v2, v89, v158
	v_exp_f32_e32 v89, v2
	v_sub_f32_e32 v2, v106, v158
	v_exp_f32_e32 v106, v2
	v_sub_f32_e32 v2, v90, v158
	v_exp_f32_e32 v90, v2
	v_sub_f32_e32 v2, v107, v158
	v_exp_f32_e32 v107, v2
	v_sub_f32_e32 v2, v91, v158
	v_exp_f32_e32 v91, v2
	v_sub_f32_e32 v2, v108, v158
	v_exp_f32_e32 v108, v2
	v_sub_f32_e32 v2, v92, v158
	v_exp_f32_e32 v92, v2
	v_sub_f32_e32 v2, v109, v158
	v_exp_f32_e32 v109, v2
	v_sub_f32_e32 v2, v93, v158
	v_exp_f32_e32 v93, v2
	v_sub_f32_e32 v2, v110, v158
	v_exp_f32_e32 v110, v2
	v_sub_f32_e32 v2, v94, v158
	v_exp_f32_e32 v94, v2
	v_sub_f32_e32 v2, v111, v158
	v_exp_f32_e32 v111, v2
	v_sub_f32_e32 v2, v95, v158
	v_exp_f32_e32 v95, v2
	v_add_f32_e32 v2, v96, v80
	v_add_f32_e32 v2, 0, v2
	v_add_f32_e32 v3, v97, v81
	v_add_f32_e32 v2, v3, v2
	v_add_f32_e32 v3, v98, v82
	v_add_f32_e32 v2, v3, v2
	v_add_f32_e32 v3, v99, v83
	v_add_f32_e32 v2, v3, v2
	v_add_f32_e32 v3, v100, v84
	v_add_f32_e32 v2, v3, v2
	v_add_f32_e32 v3, v101, v85
	v_add_f32_e32 v2, v3, v2
	v_add_f32_e32 v3, v102, v86
	v_add_f32_e32 v2, v3, v2
	v_add_f32_e32 v3, v103, v87
	v_add_f32_e32 v2, v3, v2
	v_add_f32_e32 v3, v104, v88
	v_add_f32_e32 v2, v3, v2
	v_add_f32_e32 v3, v105, v89
	v_add_f32_e32 v2, v3, v2
	v_add_f32_e32 v3, v106, v90
	v_add_f32_e32 v2, v3, v2
	v_add_f32_e32 v3, v107, v91
	v_add_f32_e32 v2, v3, v2
	v_add_f32_e32 v3, v108, v92
	v_add_f32_e32 v2, v3, v2
	v_add_f32_e32 v3, v109, v93
	v_add_f32_e32 v2, v3, v2
	v_add_f32_e32 v3, v110, v94
	v_exp_f32_e32 v0, v0
	v_add_f32_e32 v2, v3, v2
	v_add_f32_e32 v3, v111, v95
	v_add_f32_e32 v14, v3, v2
	v_mov_b32_e32 v15, v14
	v_cvt_pk_bf16_f32 v144, v96, v97
	v_cvt_pk_bf16_f32 v145, v98, v99
	v_cvt_pk_bf16_f32 v146, v100, v101
	v_cvt_pk_bf16_f32 v147, v102, v103
	v_cvt_pk_bf16_f32 v10, v104, v105
	v_cvt_pk_bf16_f32 v11, v106, v107
	v_cvt_pk_bf16_f32 v12, v108, v109
	v_cvt_pk_bf16_f32 v13, v110, v111
	v_cvt_pk_bf16_f32 v6, v80, v81
	v_cvt_pk_bf16_f32 v7, v82, v83
	v_cvt_pk_bf16_f32 v8, v84, v85
	v_cvt_pk_bf16_f32 v9, v86, v87
	v_cvt_pk_bf16_f32 v2, v88, v89
	v_cvt_pk_bf16_f32 v3, v90, v91
	v_cvt_pk_bf16_f32 v4, v92, v93
	v_cvt_pk_bf16_f32 v5, v94, v95
	s_nop 1
	v_permlane32_swap_b32_e32 v14, v15
	v_permlane32_swap_b32_e32 v144, v146
	v_permlane32_swap_b32_e32 v145, v147
	v_permlane32_swap_b32_e32 v10, v12
	v_permlane32_swap_b32_e32 v11, v13
	v_permlane32_swap_b32_e32 v6, v8
	v_permlane32_swap_b32_e32 v7, v9
	v_permlane32_swap_b32_e32 v2, v4
	v_permlane32_swap_b32_e32 v3, v5
	s_cbranch_vccnz .LBB0_1177
	s_and_saveexec_b64 s[14:15], s[0:1]
	ds_write_b32 v154, v0 offset:128
	s_or_b64 exec, exec, s[14:15]
	s_waitcnt lgkmcnt(0)
	v_add_u32_e32 v165, v151, v153
	ds_read_b128 v[166:169], v165 offset:224
	ds_read_b128 v[170:173], v165 offset:192
	ds_read_b128 v[174:177], v165 offset:160
	ds_read_b128 v[180:183], v165 offset:128
	s_waitcnt lgkmcnt(0)
	v_pk_mul_f32 v[76:77], v[76:77], v[166:167]
	v_pk_mul_f32 v[72:73], v[72:73], v[170:171]
	v_pk_mul_f32 v[68:69], v[68:69], v[174:175]
	v_pk_mul_f32 v[78:79], v[78:79], v[168:169]
	v_pk_mul_f32 v[74:75], v[74:75], v[172:173]
	v_pk_mul_f32 v[70:71], v[70:71], v[176:177]
	v_pk_mul_f32 v[66:67], v[66:67], v[182:183]
	v_pk_mul_f32 v[64:65], v[64:65], v[180:181]
	v_pk_mul_f32 v[60:61], v[60:61], v[166:167]
	v_pk_mul_f32 v[56:57], v[56:57], v[170:171]
	v_pk_mul_f32 v[52:53], v[52:53], v[174:175]
	v_pk_mul_f32 v[62:63], v[62:63], v[168:169]
	v_pk_mul_f32 v[58:59], v[58:59], v[172:173]
	v_pk_mul_f32 v[54:55], v[54:55], v[176:177]
	v_pk_mul_f32 v[50:51], v[50:51], v[182:183]
	v_pk_mul_f32 v[48:49], v[48:49], v[180:181]
	v_pk_mul_f32 v[44:45], v[44:45], v[166:167]
	v_pk_mul_f32 v[40:41], v[40:41], v[170:171]
	v_pk_mul_f32 v[36:37], v[36:37], v[174:175]
	v_pk_mul_f32 v[46:47], v[46:47], v[168:169]
	v_pk_mul_f32 v[42:43], v[42:43], v[172:173]
	v_pk_mul_f32 v[38:39], v[38:39], v[176:177]
	v_pk_mul_f32 v[34:35], v[34:35], v[182:183]
	v_pk_mul_f32 v[32:33], v[32:33], v[180:181]
	v_pk_mul_f32 v[28:29], v[28:29], v[166:167]
	v_pk_mul_f32 v[24:25], v[24:25], v[170:171]
	v_pk_mul_f32 v[20:21], v[20:21], v[174:175]
	v_pk_mul_f32 v[30:31], v[30:31], v[168:169]
	v_pk_mul_f32 v[26:27], v[26:27], v[172:173]
	v_pk_mul_f32 v[22:23], v[22:23], v[176:177]
	v_pk_mul_f32 v[18:19], v[18:19], v[182:183]
	v_pk_mul_f32 v[16:17], v[16:17], v[180:181]

.LBB0_1254:
	s_lshl_b32 s6, s45, s41
	s_or_b32 s8, s6, s37
	s_add_i32 s9, s8, s46
	v_subrev_u32_e32 v0, s39, v196
	v_cmp_le_i32_e32 vcc, s8, v197
	v_cmp_ge_i32_e64 s[6:7], s9, v0
	s_and_b64 s[28:29], vcc, s[6:7]
	s_mov_b64 s[6:7], 0
	s_and_saveexec_b64 s[26:27], s[28:29]
	s_cbranch_execz .LBB0_1258
	s_lshl_b32 s6, s50, 14
	s_add_i32 s6, s6, 0
	s_add_i32 s6, s6, 0x10000
	v_add3_u32 v0, s6, v216, v191
	v_add3_u32 v134, s6, v217, v191
	v_add3_u32 v135, s6, v218, v191
	v_add3_u32 v136, s6, v219, v191
	ds_read_b128 v[224:227], v0
	ds_read_b128 v[228:231], v134
	ds_read_b128 v[232:235], v0 offset:8192
	ds_read_b128 v[236:239], v134 offset:8192
	ds_read_b128 v[240:243], v135
	ds_read_b128 v[244:247], v135 offset:8192
	ds_read_b128 v[140:143], v136
	ds_read_b128 v[208:211], v136 offset:8192
	s_waitcnt lgkmcnt(6)
	v_mfma_f32_32x32x16_bf16 v[66:81], v[224:227], v[98:101], 0
	v_mfma_f32_32x32x16_bf16 v[66:81], v[228:231], v[106:109], v[66:81]
	ds_read_b128 v[224:227], v0 offset:128
	ds_read_b128 v[228:231], v0 offset:8320
	s_waitcnt lgkmcnt(6)
	v_mfma_f32_32x32x16_bf16 v[82:97], v[232:235], v[98:101], 0
	v_mfma_f32_32x32x16_bf16 v[82:97], v[236:239], v[106:109], v[82:97]
	ds_read_b128 v[232:235], v134 offset:128
	ds_read_b128 v[236:239], v134 offset:8320
	s_waitcnt lgkmcnt(6)
	v_mfma_f32_32x32x16_bf16 v[66:81], v[240:243], v[114:117], v[66:81]
	v_mfma_f32_32x32x16_bf16 v[82:97], v[244:247], v[114:117], v[82:97]
	ds_read_b128 v[240:243], v135 offset:128
	ds_read_b128 v[244:247], v135 offset:8320
	s_waitcnt lgkmcnt(6)
	v_mfma_f32_32x32x16_bf16 v[66:81], v[140:143], v[122:125], v[66:81]
	v_mfma_f32_32x32x16_bf16 v[82:97], v[208:211], v[122:125], v[82:97]
	ds_read_b128 v[140:143], v136 offset:128
	ds_read_b128 v[208:211], v136 offset:8320
	v_cmp_gt_i32_e32 vcc, s9, v196
	s_xor_b64 s[6:7], s[12:13], -1
	s_or_b64 s[6:7], s[6:7], vcc
	v_subrev_u32_e32 v0, s39, v197
	v_cmp_lt_i32_e32 vcc, s8, v0
	s_or_b64 s[6:7], s[6:7], vcc
	s_waitcnt lgkmcnt(6)
	v_mfma_f32_32x32x16_bf16 v[66:81], v[224:227], v[102:105], v[66:81]
	v_mfma_f32_32x32x16_bf16 v[82:97], v[228:231], v[102:105], v[82:97]
	s_waitcnt lgkmcnt(4)
	v_mfma_f32_32x32x16_bf16 v[66:81], v[232:235], v[110:113], v[66:81]
	v_mfma_f32_32x32x16_bf16 v[82:97], v[236:239], v[110:113], v[82:97]
	s_waitcnt lgkmcnt(2)
	v_mfma_f32_32x32x16_bf16 v[66:81], v[240:243], v[118:121], v[66:81]
	v_mfma_f32_32x32x16_bf16 v[82:97], v[244:247], v[118:121], v[82:97]
	s_waitcnt lgkmcnt(0)
	v_mfma_f32_32x32x16_bf16 v[66:81], v[140:143], v[126:129], v[66:81]
	v_mfma_f32_32x32x16_bf16 v[82:97], v[208:211], v[126:129], v[82:97]
	s_nop 1
	s_and_saveexec_b64 s[28:29], s[6:7]
	s_cbranch_execz .LBB0_1257
	v_add_u32_e32 v0, s49, v222
	v_lshl_add_u32 v130, v0, s41, v223
	v_subrev_u32_e32 v131, s2, v130
	v_cmp_ge_u32_e32 vcc, s39, v130
	v_cmp_ge_u32_e64 s[6:7], s39, v131
	s_and_b64 vcc, s[4:5], vcc
	v_add_u32_e32 v130, -1, v0
	v_cndmask_b32_e32 v66, v214, v66, vcc
	s_and_b64 vcc, s[4:5], s[6:7]
	v_lshl_add_u32 v130, v130, s41, v223
	v_cndmask_b32_e32 v82, v214, v82, vcc
	v_subrev_u32_e32 v131, s2, v130
	v_cmp_ge_u32_e32 vcc, s39, v130
	v_and_b32_e32 v130, s40, v130
	v_cmp_eq_u32_e64 s[6:7], 0, v130
	v_cmp_ge_u32_e64 s[8:9], s39, v131
	s_and_b64 vcc, vcc, s[6:7]
	v_add_u32_e32 v130, -2, v0
	v_cndmask_b32_e32 v67, v214, v67, vcc
	s_and_b64 vcc, s[8:9], s[6:7]
	v_lshl_add_u32 v130, v130, s41, v223
	v_cndmask_b32_e32 v83, v214, v83, vcc
	v_subrev_u32_e32 v131, s2, v130
	v_cmp_ge_u32_e32 vcc, s39, v130
	v_and_b32_e32 v130, s40, v130
	v_cmp_eq_u32_e64 s[6:7], 0, v130
	v_cmp_ge_u32_e64 s[8:9], s39, v131
	s_and_b64 vcc, vcc, s[6:7]
	v_add_u32_e32 v130, -3, v0
	v_cndmask_b32_e32 v68, v214, v68, vcc
	s_and_b64 vcc, s[8:9], s[6:7]
	v_lshl_add_u32 v130, v130, s41, v223
	v_cndmask_b32_e32 v84, v214, v84, vcc
	v_subrev_u32_e32 v131, s2, v130
	v_cmp_ge_u32_e32 vcc, s39, v130
	v_and_b32_e32 v130, s40, v130
	v_cmp_eq_u32_e64 s[6:7], 0, v130
	v_cmp_ge_u32_e64 s[8:9], s39, v131
	s_and_b64 vcc, vcc, s[6:7]
	v_add_u32_e32 v130, -8, v0
	v_cndmask_b32_e32 v69, v214, v69, vcc
	s_and_b64 vcc, s[8:9], s[6:7]
	v_lshl_add_u32 v130, v130, s41, v223
	v_cndmask_b32_e32 v85, v214, v85, vcc
	v_subrev_u32_e32 v131, s2, v130
	v_cmp_ge_u32_e32 vcc, s39, v130
	v_cmp_ge_u32_e64 s[6:7], s39, v131
	s_and_b64 vcc, s[4:5], vcc
	v_add_u32_e32 v130, -9, v0
	v_cndmask_b32_e32 v70, v214, v70, vcc
	s_and_b64 vcc, s[4:5], s[6:7]
	v_lshl_add_u32 v130, v130, s41, v223
	v_cndmask_b32_e32 v86, v214, v86, vcc
	v_subrev_u32_e32 v131, s2, v130
	v_cmp_ge_u32_e32 vcc, s39, v130
	v_and_b32_e32 v130, s40, v130
	v_cmp_eq_u32_e64 s[6:7], 0, v130
	v_cmp_ge_u32_e64 s[8:9], s39, v131
	s_and_b64 vcc, vcc, s[6:7]
	v_add_u32_e32 v130, -10, v0
	v_cndmask_b32_e32 v71, v214, v71, vcc
	s_and_b64 vcc, s[8:9], s[6:7]
	v_lshl_add_u32 v130, v130, s41, v223
	v_cndmask_b32_e32 v87, v214, v87, vcc
	v_subrev_u32_e32 v131, s2, v130
	v_cmp_ge_u32_e32 vcc, s39, v130
	v_and_b32_e32 v130, s40, v130
	v_cmp_eq_u32_e64 s[6:7], 0, v130
	v_cmp_ge_u32_e64 s[8:9], s39, v131
	s_and_b64 vcc, vcc, s[6:7]
	v_add_u32_e32 v130, -11, v0
	v_cndmask_b32_e32 v72, v214, v72, vcc
	s_and_b64 vcc, s[8:9], s[6:7]
	v_lshl_add_u32 v130, v130, s41, v223
	v_cndmask_b32_e32 v88, v214, v88, vcc
	v_subrev_u32_e32 v131, s2, v130
	v_cmp_ge_u32_e32 vcc, s39, v130
	v_and_b32_e32 v130, s40, v130
	v_cmp_eq_u32_e64 s[6:7], 0, v130
	v_cmp_ge_u32_e64 s[8:9], s39, v131
	s_and_b64 vcc, vcc, s[6:7]
	v_add_u32_e32 v130, -16, v0
	v_cndmask_b32_e32 v73, v214, v73, vcc
	s_and_b64 vcc, s[8:9], s[6:7]
	v_lshl_add_u32 v130, v130, s41, v223
	v_cndmask_b32_e32 v89, v214, v89, vcc
	v_subrev_u32_e32 v131, s2, v130
	v_cmp_ge_u32_e32 vcc, s39, v130
	v_cmp_ge_u32_e64 s[6:7], s39, v131
	s_and_b64 vcc, s[4:5], vcc
	v_subrev_u32_e32 v130, 17, v0
	v_cndmask_b32_e32 v74, v214, v74, vcc
	s_and_b64 vcc, s[4:5], s[6:7]
	v_lshl_add_u32 v130, v130, s41, v223
	v_cndmask_b32_e32 v90, v214, v90, vcc
	v_subrev_u32_e32 v131, s2, v130
	v_cmp_ge_u32_e32 vcc, s39, v130
	v_and_b32_e32 v130, s40, v130
	v_cmp_eq_u32_e64 s[6:7], 0, v130
	v_cmp_ge_u32_e64 s[8:9], s39, v131
	s_and_b64 vcc, vcc, s[6:7]
	v_subrev_u32_e32 v130, 18, v0
	v_cndmask_b32_e32 v75, v214, v75, vcc
	s_and_b64 vcc, s[8:9], s[6:7]
	v_lshl_add_u32 v130, v130, s41, v223
	v_cndmask_b32_e32 v91, v214, v91, vcc
	v_subrev_u32_e32 v131, s2, v130
	v_cmp_ge_u32_e32 vcc, s39, v130
	v_and_b32_e32 v130, s40, v130
	v_cmp_eq_u32_e64 s[6:7], 0, v130
	v_cmp_ge_u32_e64 s[8:9], s39, v131
	s_and_b64 vcc, vcc, s[6:7]
	v_subrev_u32_e32 v130, 19, v0
	v_cndmask_b32_e32 v76, v214, v76, vcc
	s_and_b64 vcc, s[8:9], s[6:7]
	v_lshl_add_u32 v130, v130, s41, v223
	v_cndmask_b32_e32 v92, v214, v92, vcc
	v_subrev_u32_e32 v131, s2, v130
	v_cmp_ge_u32_e32 vcc, s39, v130
	v_and_b32_e32 v130, s40, v130
	v_cmp_eq_u32_e64 s[6:7], 0, v130
	v_cmp_ge_u32_e64 s[8:9], s39, v131
	s_and_b64 vcc, vcc, s[6:7]
	v_subrev_u32_e32 v130, 24, v0
	v_cndmask_b32_e32 v77, v214, v77, vcc
	s_and_b64 vcc, s[8:9], s[6:7]
	v_lshl_add_u32 v130, v130, s41, v223
	v_cndmask_b32_e32 v93, v214, v93, vcc
	v_subrev_u32_e32 v131, s2, v130
	v_cmp_ge_u32_e32 vcc, s39, v130
	v_cmp_ge_u32_e64 s[6:7], s39, v131
	s_and_b64 vcc, s[4:5], vcc
	v_subrev_u32_e32 v130, 25, v0
	v_cndmask_b32_e32 v78, v214, v78, vcc
	s_and_b64 vcc, s[4:5], s[6:7]
	v_lshl_add_u32 v130, v130, s41, v223
	v_cndmask_b32_e32 v94, v214, v94, vcc
	v_subrev_u32_e32 v131, s2, v130
	v_cmp_ge_u32_e32 vcc, s39, v130
	v_and_b32_e32 v130, s40, v130
	v_cmp_eq_u32_e64 s[6:7], 0, v130
	v_cmp_ge_u32_e64 s[8:9], s39, v131
	s_and_b64 vcc, vcc, s[6:7]
	v_subrev_u32_e32 v130, 26, v0
	v_cndmask_b32_e32 v79, v214, v79, vcc
	s_and_b64 vcc, s[8:9], s[6:7]
	v_lshl_add_u32 v130, v130, s41, v223
	v_cndmask_b32_e32 v95, v214, v95, vcc
	v_subrev_u32_e32 v131, s2, v130
	v_cmp_ge_u32_e32 vcc, s39, v130
	v_and_b32_e32 v130, s40, v130
	v_cmp_eq_u32_e64 s[6:7], 0, v130
	v_cmp_ge_u32_e64 s[8:9], s39, v131
	s_and_b64 vcc, vcc, s[6:7]
	v_subrev_u32_e32 v0, 27, v0
	v_cndmask_b32_e32 v80, v214, v80, vcc
	s_and_b64 vcc, s[8:9], s[6:7]
	v_lshl_add_u32 v0, v0, s41, v223
	v_cndmask_b32_e32 v96, v214, v96, vcc
	v_subrev_u32_e32 v130, s2, v0
	v_cmp_ge_u32_e32 vcc, s39, v0
	v_and_b32_e32 v0, s40, v0
	v_cmp_eq_u32_e64 s[6:7], 0, v0
	v_cmp_ge_u32_e64 s[8:9], s39, v130
	s_and_b64 vcc, vcc, s[6:7]
	v_cndmask_b32_e32 v81, v214, v81, vcc
	s_and_b64 vcc, s[8:9], s[6:7]
	v_cndmask_b32_e32 v97, v214, v97, vcc
